# A2/A3 lazy-rescale test: cross-half ds_bpermute max moved into the rare rescale path; branch tests per-lane max directly (any-lane equivalent)
# baseline (speedup 1.0000x reference)
; DI float shx(float v, int o, int lane) { return __int_as_float(__builtin_amdgcn_ds_bpermute((lane ^ o) << 2, __float_as_int(v))); }
;     ...
;             float mx = -1e30f;
; #pragma unroll
;             for (int kb2 = 0; kb2 < NKB; ++kb2)
; #pragma unroll
;                 for (int i = 0; i < 16; ++i) mx = __builtin_fmaxf(mx, sv[kb2][i]);
;             mx = __builtin_fmaxf(mx, shx(mx, 32, lane));
;             if (__ballot(mx > 8.0f)) {
;                 const float delta = __builtin_fmaxf(mx, 0.f);
;                 const float alpha = __builtin_amdgcn_exp2f(-delta);
;                 nm_run -= delta; l_run *= alpha;
; #pragma unroll
;                 for (int kb2 = 0; kb2 < NKB; ++kb2)
; #pragma unroll
;                     for (int i = 0; i < 16; ++i) sv[kb2][i] -= delta;
; #pragma unroll
;                 for (int db = 0; db < NDB; ++db)
; #pragma unroll
;                     for (int i = 0; i < 16; ++i) ot[db][i] *= alpha;
;             }
.LBB0_505:
	s_nop 9
	v_max3_f32 v65, v82, s61, v83
	v_max3_f32 v65, v65, v84, v85
	v_max3_f32 v65, v65, v86, v87
	v_max3_f32 v65, v65, v88, v89
	v_max3_f32 v65, v65, v90, v91
	v_max3_f32 v65, v65, v92, v93
	v_max3_f32 v65, v65, v94, v95
	v_max3_f32 v65, v65, v96, v97
	v_max3_f32 v65, v65, v66, v67
	v_max3_f32 v65, v65, v68, v69
	v_max3_f32 v65, v65, v70, v71
	v_max3_f32 v65, v65, v72, v73
	v_max3_f32 v65, v65, v74, v75
	v_max3_f32 v65, v65, v76, v77
	v_max3_f32 v65, v65, v78, v79
	v_max3_f32 v65, v65, v80, v81
	v_cmp_lt_f32_e32 vcc, s33, v65
	s_cbranch_vccz .LBB0_500
	ds_bpermute_b32 v196, v99, v65
	s_waitcnt lgkmcnt(0)
	v_max_f32_e32 v196, v196, v196
	v_max_f32_e32 v65, v65, v196
	v_max_f32_e32 v65, v65, v65
	v_max_f32_e32 v196, 0, v65
	v_exp_f32_e64 v218, -v196
	v_sub_f32_e32 v64, v64, v196
	v_pk_add_f32 v[82:83], v[82:83], v[196:197] op_sel_hi:[1,0] neg_lo:[0,1] neg_hi:[0,1]
	v_pk_add_f32 v[84:85], v[84:85], v[196:197] op_sel_hi:[1,0] neg_lo:[0,1] neg_hi:[0,1]
	v_pk_add_f32 v[86:87], v[86:87], v[196:197] op_sel_hi:[1,0] neg_lo:[0,1] neg_hi:[0,1]
	v_pk_add_f32 v[88:89], v[88:89], v[196:197] op_sel_hi:[1,0] neg_lo:[0,1] neg_hi:[0,1]
	v_pk_add_f32 v[90:91], v[90:91], v[196:197] op_sel_hi:[1,0] neg_lo:[0,1] neg_hi:[0,1]
	v_pk_add_f32 v[92:93], v[92:93], v[196:197] op_sel_hi:[1,0] neg_lo:[0,1] neg_hi:[0,1]
	v_pk_add_f32 v[94:95], v[94:95], v[196:197] op_sel_hi:[1,0] neg_lo:[0,1] neg_hi:[0,1]
	v_pk_add_f32 v[96:97], v[96:97], v[196:197] op_sel_hi:[1,0] neg_lo:[0,1] neg_hi:[0,1]
	v_pk_add_f32 v[66:67], v[66:67], v[196:197] op_sel_hi:[1,0] neg_lo:[0,1] neg_hi:[0,1]
	v_pk_add_f32 v[68:69], v[68:69], v[196:197] op_sel_hi:[1,0] neg_lo:[0,1] neg_hi:[0,1]
	v_pk_add_f32 v[70:71], v[70:71], v[196:197] op_sel_hi:[1,0] neg_lo:[0,1] neg_hi:[0,1]
	v_pk_add_f32 v[72:73], v[72:73], v[196:197] op_sel_hi:[1,0] neg_lo:[0,1] neg_hi:[0,1]
	v_pk_add_f32 v[74:75], v[74:75], v[196:197] op_sel_hi:[1,0] neg_lo:[0,1] neg_hi:[0,1]
	v_pk_add_f32 v[76:77], v[76:77], v[196:197] op_sel_hi:[1,0] neg_lo:[0,1] neg_hi:[0,1]
	v_pk_add_f32 v[78:79], v[78:79], v[196:197] op_sel_hi:[1,0] neg_lo:[0,1] neg_hi:[0,1]
	v_pk_add_f32 v[80:81], v[80:81], v[196:197] op_sel_hi:[1,0] neg_lo:[0,1] neg_hi:[0,1]
	v_pk_mul_f32 v[14:15], v[14:15], v[218:219] op_sel_hi:[1,0]
	v_pk_mul_f32 v[12:13], v[12:13], v[218:219] op_sel_hi:[1,0]
	v_pk_mul_f32 v[10:11], v[10:11], v[218:219] op_sel_hi:[1,0]
	v_pk_mul_f32 v[8:9], v[8:9], v[218:219] op_sel_hi:[1,0]
	v_pk_mul_f32 v[6:7], v[6:7], v[218:219] op_sel_hi:[1,0]
	v_pk_mul_f32 v[4:5], v[4:5], v[218:219] op_sel_hi:[1,0]
	v_pk_mul_f32 v[2:3], v[2:3], v[218:219] op_sel_hi:[1,0]
	v_pk_mul_f32 v[0:1], v[0:1], v[218:219] op_sel_hi:[1,0]
	v_pk_mul_f32 v[62:63], v[62:63], v[218:219] op_sel_hi:[1,0]
	v_pk_mul_f32 v[60:61], v[60:61], v[218:219] op_sel_hi:[1,0]
	v_pk_mul_f32 v[58:59], v[58:59], v[218:219] op_sel_hi:[1,0]
	v_pk_mul_f32 v[56:57], v[56:57], v[218:219] op_sel_hi:[1,0]
	v_pk_mul_f32 v[54:55], v[54:55], v[218:219] op_sel_hi:[1,0]
	v_pk_mul_f32 v[52:53], v[52:53], v[218:219] op_sel_hi:[1,0]
	v_pk_mul_f32 v[50:51], v[50:51], v[218:219] op_sel_hi:[1,0]
	v_pk_mul_f32 v[48:49], v[48:49], v[218:219] op_sel_hi:[1,0]
	v_pk_mul_f32 v[46:47], v[46:47], v[218:219] op_sel_hi:[1,0]
	v_pk_mul_f32 v[44:45], v[44:45], v[218:219] op_sel_hi:[1,0]
	v_pk_mul_f32 v[42:43], v[42:43], v[218:219] op_sel_hi:[1,0]
	v_pk_mul_f32 v[40:41], v[40:41], v[218:219] op_sel_hi:[1,0]
	v_pk_mul_f32 v[38:39], v[38:39], v[218:219] op_sel_hi:[1,0]
	v_pk_mul_f32 v[36:37], v[36:37], v[218:219] op_sel_hi:[1,0]
	v_pk_mul_f32 v[34:35], v[34:35], v[218:219] op_sel_hi:[1,0]
	v_pk_mul_f32 v[32:33], v[32:33], v[218:219] op_sel_hi:[1,0]
	v_pk_mul_f32 v[30:31], v[30:31], v[218:219] op_sel_hi:[1,0]
	v_pk_mul_f32 v[28:29], v[28:29], v[218:219] op_sel_hi:[1,0]
	v_pk_mul_f32 v[26:27], v[26:27], v[218:219] op_sel_hi:[1,0]
	v_pk_mul_f32 v[24:25], v[24:25], v[218:219] op_sel_hi:[1,0]
	v_pk_mul_f32 v[22:23], v[22:23], v[218:219] op_sel_hi:[1,0]
	v_pk_mul_f32 v[20:21], v[20:21], v[218:219] op_sel_hi:[1,0]
	v_pk_mul_f32 v[18:19], v[18:19], v[218:219] op_sel_hi:[1,0]
	v_pk_mul_f32 v[16:17], v[16:17], v[218:219] op_sel_hi:[1,0]
	v_mul_f32_e32 v212, v212, v218
	s_branch .LBB0_500

; #define LAS __attribute__((address_space(3)))
; #define MFMA32(a, b, c) __builtin_amdgcn_mfma_f32_32x32x16_bf16((a), (b), (c), 0, 0, 0)
;     ...
;         const int key0 = kt * KT + sub * 32 * NKB;
;         if ((MODE == 0 || key0 <= q0 + 31) && PV != 2) {
;             unsigned long long mw[NKB / 2];
;             if (MODE == 0) {
; #pragma unroll
;                 for (int w = 0; w < NKB / 2; ++w) mw[w] = MASK64[(rowbase + q0 + r) * 32 + (key0 >> 6) + w];
;             }
;             f32x16 sv[NKB];
; #pragma unroll
;             for (int kb2 = 0; kb2 < NKB; ++kb2)
; #pragma unroll
;                 for (int i = 0; i < 16; ++i) sv[kb2][i] = nm_run;
;             const LAS unsigned char* kb_ = lds + st * STAGE + koff + sub * 32 * NKB * KP;
; #pragma unroll
;             for (int kh = 0; kh < 2; ++kh) {
;                 bf16x8 kfr[2][NKB];
; #pragma unroll
;                 for (int k2 = 0; k2 < 2; ++k2)
; #pragma unroll
;                     for (int kb2 = 0; kb2 < NKB; ++kb2) kfr[k2][kb2] = *(const LAS bf16x8*)(kb_ + (32 * kb2 + r) * KP + (2 * kh + k2) * 32 + h * 16);
;                 if (NKB == 2) asm volatile("" : "+v"(kfr[0][0]), "+v"(kfr[0][1]), "+v"(kfr[1][0]), "+v"(kfr[1][1]));
;                 else asm volatile("" : "+v"(kfr[0][0]), "+v"(kfr[0][1]), "+v"(kfr[0][NKB - 2]), "+v"(kfr[0][NKB - 1]), "+v"(kfr[1][0]), "+v"(kfr[1][1]), "+v"(kfr[1][NKB - 2]), "+v"(kfr[1][NKB - 1]));
; #pragma unroll
;                 for (int k2 = 0; k2 < 2; ++k2)
; #pragma unroll
;                     for (int kb2 = 0; kb2 < NKB; ++kb2) sv[kb2] = MFMA32(kfr[k2][kb2], qf[2 * kh + k2], sv[kb2]);
;             }
;             if (MODE == 0) {
; #pragma unroll
;                 for (int kb2 = 0; kb2 < NKB; ++kb2) {
;                     const unsigned wsel = ((kb2 & 1) ? (unsigned)(mw[kb2 >> 1] >> 32) : (unsigned)mw[kb2 >> 1]) >> (4 * h);
; #pragma unroll
;                     for (int i = 0; i < 16; ++i) { const int cb = (i & 3) + 8 * (i >> 2); if (!((wsel >> cb) & 1u)) sv[kb2][i] = -1e30f; }
;                 }
;             } else if (key0 + 32 * NKB - 1 > q0) {
.LBB0_522:
	v_lshl_add_u64 v[34:35], s[0:1], 0, v[166:167]
	v_add_co_u32_e32 v34, vcc, 0x1d600000, v34
	s_and_b32 s7, s6, 1
	s_nop 0
	v_addc_co_u32_e32 v35, vcc, 0, v35, vcc
	global_load_dwordx4 v[132:135], v[34:35], off
	s_mul_i32 s9, s7, 0x8a00
	s_add_i32 s9, s9, 0
	v_add3_u32 v185, s9, v180, v182
	ds_read_b128 v[186:189], v185 offset:13856
	ds_read_b128 v[190:193], v185 offset:9248
	ds_read_b128 v[200:203], v185 offset:4640
	ds_read_b128 v[204:207], v185 offset:13824
	ds_read_b128 v[208:211], v185 offset:9216
	ds_read_b128 v[48:51], v185 offset:4608
	ds_read_b128 v[52:55], v185
	ds_read_b128 v[212:215], v185 offset:32
	v_mov_b32_e32 v33, v32
	v_mov_b32_e32 v34, v32
	v_mov_b32_e32 v35, v32
	v_mov_b32_e32 v36, v32
	v_mov_b32_e32 v37, v32
	v_mov_b32_e32 v38, v32
	v_mov_b32_e32 v39, v32
	v_mov_b32_e32 v40, v32
	v_mov_b32_e32 v41, v32
	v_mov_b32_e32 v42, v32
	v_mov_b32_e32 v43, v32
	v_mov_b32_e32 v44, v32
	v_mov_b32_e32 v45, v32
	v_mov_b32_e32 v46, v32
	v_mov_b32_e32 v47, v32
	s_waitcnt lgkmcnt(0)
	s_nop 0
	v_mfma_f32_32x32x16_bf16 v[82:97], v[52:55], v[100:103], v[32:47]
	v_mfma_f32_32x32x16_bf16 v[66:81], v[48:51], v[100:103], v[32:47]
	v_mfma_f32_32x32x16_bf16 v[50:65], v[208:211], v[100:103], v[32:47]
	v_mov_b64_e32 v[48:49], v[46:47]
	s_nop 5
	v_mov_b64_e32 v[46:47], v[44:45]
	v_mov_b64_e32 v[44:45], v[42:43]
	v_mov_b64_e32 v[42:43], v[40:41]
	v_mov_b64_e32 v[40:41], v[38:39]
	v_mov_b64_e32 v[38:39], v[36:37]
	v_mov_b64_e32 v[36:37], v[34:35]
	v_mov_b64_e32 v[34:35], v[32:33]
	v_mfma_f32_32x32x16_bf16 v[82:97], v[212:215], v[104:107], v[82:97]
	s_waitcnt vmcnt(0)
	v_lshrrev_b32_e32 v132, v150, v132
	v_lshrrev_b32_e32 v133, v150, v133
	v_lshrrev_b32_e32 v134, v150, v134
	v_lshrrev_b32_e32 v135, v150, v135
	v_mfma_f32_32x32x16_bf16 v[34:49], v[204:207], v[100:103], v[34:49]
	v_mfma_f32_32x32x16_bf16 v[66:81], v[200:203], v[104:107], v[66:81]
	v_mfma_f32_32x32x16_bf16 v[50:65], v[190:193], v[104:107], v[50:65]
	v_mfma_f32_32x32x16_bf16 v[34:49], v[186:189], v[104:107], v[34:49]
	ds_read_b128 v[186:189], v185 offset:13920
	ds_read_b128 v[190:193], v185 offset:9312
	ds_read_b128 v[200:203], v185 offset:4704
	ds_read_b128 v[204:207], v185 offset:13888
	ds_read_b128 v[208:211], v185 offset:9280
	ds_read_b128 v[212:215], v185 offset:4672
	ds_read_b128 v[216:219], v185 offset:64
	ds_read_b128 v[220:223], v185 offset:96
	s_waitcnt lgkmcnt(0)
	s_nop 0
	v_mfma_f32_32x32x16_bf16 v[82:97], v[216:219], v[108:111], v[82:97]
	v_mfma_f32_32x32x16_bf16 v[82:97], v[220:223], v[112:115], v[82:97]
	v_mfma_f32_32x32x16_bf16 v[66:81], v[212:215], v[108:111], v[66:81]
	s_nop 10
	v_bfe_i32 v224, v132, 0, 1
	v_bfi_b32 v82, v224, v82, v235
	v_bfe_i32 v224, v132, 1, 1
	v_bfi_b32 v83, v224, v83, v235
	v_mfma_f32_32x32x16_bf16 v[66:81], v[200:203], v[112:115], v[66:81]
	v_bfe_i32 v224, v132, 2, 1
	v_bfi_b32 v84, v224, v84, v235
	v_bfe_i32 v224, v132, 3, 1
	v_bfi_b32 v85, v224, v85, v235
	v_mfma_f32_32x32x16_bf16 v[50:65], v[208:211], v[108:111], v[50:65]
	v_bfe_i32 v224, v132, 8, 1
	v_bfi_b32 v86, v224, v86, v235
	v_bfe_i32 v224, v132, 9, 1
	v_bfi_b32 v87, v224, v87, v235
	v_mfma_f32_32x32x16_bf16 v[50:65], v[190:193], v[112:115], v[50:65]
	v_bfe_i32 v224, v132, 10, 1
	v_bfi_b32 v88, v224, v88, v235
	v_bfe_i32 v224, v132, 11, 1
	v_bfi_b32 v89, v224, v89, v235
	v_mfma_f32_32x32x16_bf16 v[34:49], v[204:207], v[108:111], v[34:49]
	v_bfe_i32 v224, v132, 16, 1
	v_bfi_b32 v90, v224, v90, v235
	v_bfe_i32 v224, v132, 17, 1
	v_bfi_b32 v91, v224, v91, v235
	v_mfma_f32_32x32x16_bf16 v[34:49], v[186:189], v[112:115], v[34:49]
	v_bfe_i32 v224, v132, 18, 1
	v_bfi_b32 v92, v224, v92, v235
	v_bfe_i32 v224, v132, 19, 1
	v_bfi_b32 v93, v224, v93, v235
	v_bfe_i32 v224, v132, 24, 1
	v_bfi_b32 v94, v224, v94, v235
	v_bfe_i32 v224, v132, 25, 1
	v_bfi_b32 v95, v224, v95, v235
	v_bfe_i32 v224, v132, 26, 1
	v_bfi_b32 v96, v224, v96, v235
	v_bfe_i32 v224, v132, 27, 1
	v_bfi_b32 v97, v224, v97, v235
	v_bfe_i32 v224, v133, 0, 1
	v_bfi_b32 v66, v224, v66, v235
	v_bfe_i32 v224, v133, 1, 1
	v_bfi_b32 v67, v224, v67, v235
	v_bfe_i32 v224, v133, 2, 1
	v_bfi_b32 v68, v224, v68, v235
	v_bfe_i32 v224, v133, 3, 1
	v_bfi_b32 v69, v224, v69, v235
	v_bfe_i32 v224, v133, 8, 1
	v_bfi_b32 v70, v224, v70, v235
	v_bfe_i32 v224, v133, 9, 1
	v_bfi_b32 v71, v224, v71, v235
	v_bfe_i32 v224, v133, 10, 1
	v_bfi_b32 v72, v224, v72, v235
	v_bfe_i32 v224, v133, 11, 1
	v_bfi_b32 v73, v224, v73, v235
	v_bfe_i32 v224, v133, 16, 1
	v_bfi_b32 v74, v224, v74, v235
	v_bfe_i32 v224, v133, 17, 1
	v_bfi_b32 v75, v224, v75, v235
	v_bfe_i32 v224, v133, 18, 1
	v_bfi_b32 v76, v224, v76, v235
	v_bfe_i32 v224, v133, 19, 1
	v_bfi_b32 v77, v224, v77, v235
	v_bfe_i32 v224, v133, 24, 1
	v_bfi_b32 v78, v224, v78, v235
	v_bfe_i32 v224, v133, 25, 1
	v_bfi_b32 v79, v224, v79, v235
	v_bfe_i32 v224, v133, 26, 1
	v_bfi_b32 v80, v224, v80, v235
	v_bfe_i32 v224, v133, 27, 1
	v_bfi_b32 v81, v224, v81, v235
	v_bfe_i32 v224, v134, 0, 1
	v_bfi_b32 v50, v224, v50, v235
	v_bfe_i32 v224, v134, 1, 1
	v_bfi_b32 v51, v224, v51, v235
	v_bfe_i32 v224, v134, 2, 1
	v_bfi_b32 v52, v224, v52, v235
	v_bfe_i32 v224, v134, 3, 1
	v_bfi_b32 v53, v224, v53, v235
	v_bfe_i32 v224, v134, 8, 1
	v_bfi_b32 v54, v224, v54, v235
	v_bfe_i32 v224, v134, 9, 1
	v_bfi_b32 v55, v224, v55, v235
	v_bfe_i32 v224, v134, 10, 1
	v_bfi_b32 v56, v224, v56, v235
	v_bfe_i32 v224, v134, 11, 1
	v_bfi_b32 v57, v224, v57, v235
	v_bfe_i32 v224, v134, 16, 1
	v_bfi_b32 v58, v224, v58, v235
	v_bfe_i32 v224, v134, 17, 1
	v_bfi_b32 v59, v224, v59, v235
	v_bfe_i32 v224, v134, 18, 1
	v_bfi_b32 v60, v224, v60, v235
	v_bfe_i32 v224, v134, 19, 1
	v_bfi_b32 v61, v224, v61, v235
	v_bfe_i32 v224, v134, 24, 1
; DI float shx(float v, int o, int lane) { return __int_as_float(__builtin_amdgcn_ds_bpermute((lane ^ o) << 2, __float_as_int(v))); }
; DI int crow(int i, int h) { return (i & 3) + 8 * (i >> 2) + 4 * h; }
;     ...
;             if (MODE == 0) {
; #pragma unroll
;                 for (int kb2 = 0; kb2 < NKB; ++kb2) {
;                     const unsigned wsel = ((kb2 & 1) ? (unsigned)(mw[kb2 >> 1] >> 32) : (unsigned)mw[kb2 >> 1]) >> (4 * h);
; #pragma unroll
;                     for (int i = 0; i < 16; ++i) { const int cb = (i & 3) + 8 * (i >> 2); if (!((wsel >> cb) & 1u)) sv[kb2][i] = -1e30f; }
;                 }
;             } else if (key0 + 32 * NKB - 1 > q0) {
;                 const int qq = q0 + r;
; #pragma unroll
;                 for (int kb2 = 0; kb2 < NKB; ++kb2)
; #pragma unroll
;                     for (int i = 0; i < 16; ++i) { if (key0 + 32 * kb2 + crow(i, h) > qq) sv[kb2][i] = -1e30f; }
;             }
;             float mx = -1e30f;
; #pragma unroll
;             for (int kb2 = 0; kb2 < NKB; ++kb2)
; #pragma unroll
;                 for (int i = 0; i < 16; ++i) mx = __builtin_fmaxf(mx, sv[kb2][i]);
;             mx = __builtin_fmaxf(mx, shx(mx, 32, lane));
;             if (__ballot(mx > 8.0f)) {
;                 const float delta = __builtin_fmaxf(mx, 0.f);
;                 const float alpha = __builtin_amdgcn_exp2f(-delta);
;                 nm_run -= delta; l_run *= alpha;
; #pragma unroll
;                 for (int kb2 = 0; kb2 < NKB; ++kb2)
; #pragma unroll
;                     for (int i = 0; i < 16; ++i) sv[kb2][i] -= delta;
; #pragma unroll
;                 for (int db = 0; db < NDB; ++db)
; #pragma unroll
;                     for (int i = 0; i < 16; ++i) ot[db][i] *= alpha;
;             }
	v_bfi_b32 v62, v224, v62, v235
	v_bfe_i32 v224, v134, 25, 1
	v_bfi_b32 v63, v224, v63, v235
	v_bfe_i32 v224, v134, 26, 1
	v_bfi_b32 v64, v224, v64, v235
	v_bfe_i32 v224, v134, 27, 1
	v_bfi_b32 v65, v224, v65, v235
	v_bfe_i32 v224, v135, 0, 1
	v_bfi_b32 v34, v224, v34, v235
	v_bfe_i32 v224, v135, 1, 1
	v_bfi_b32 v35, v224, v35, v235
	v_bfe_i32 v224, v135, 2, 1
	v_bfi_b32 v36, v224, v36, v235
	v_bfe_i32 v224, v135, 3, 1
	v_bfi_b32 v37, v224, v37, v235
	v_bfe_i32 v224, v135, 8, 1
	v_bfi_b32 v38, v224, v38, v235
	v_bfe_i32 v224, v135, 9, 1
	v_bfi_b32 v39, v224, v39, v235
	v_bfe_i32 v224, v135, 10, 1
	v_bfi_b32 v40, v224, v40, v235
	v_bfe_i32 v224, v135, 11, 1
	v_bfi_b32 v41, v224, v41, v235
	v_bfe_i32 v224, v135, 16, 1
	v_bfi_b32 v42, v224, v42, v235
	v_bfe_i32 v224, v135, 17, 1
	v_bfi_b32 v43, v224, v43, v235
	v_bfe_i32 v224, v135, 18, 1
	v_bfi_b32 v44, v224, v44, v235
	v_bfe_i32 v224, v135, 19, 1
	v_bfi_b32 v45, v224, v45, v235
	v_bfe_i32 v224, v135, 24, 1
	v_bfi_b32 v46, v224, v46, v235
	v_bfe_i32 v224, v135, 25, 1
	v_bfi_b32 v47, v224, v47, v235
	v_bfe_i32 v224, v135, 26, 1
	v_bfi_b32 v48, v224, v48, v235
	v_max3_f32 v33, v82, s61, v83
	v_max3_f32 v33, v33, v84, v85
	v_max3_f32 v33, v33, v86, v87
	v_max3_f32 v33, v33, v88, v89
	v_max3_f32 v33, v33, v90, v91
	v_max3_f32 v33, v33, v92, v93
	v_max3_f32 v33, v33, v94, v95
	v_max3_f32 v33, v33, v96, v97
	v_max3_f32 v33, v33, v66, v67
	v_max3_f32 v33, v33, v68, v69
	v_max3_f32 v33, v33, v70, v71
	v_max3_f32 v33, v33, v72, v73
	v_max3_f32 v33, v33, v74, v75
	v_max3_f32 v33, v33, v76, v77
	v_max3_f32 v33, v33, v78, v79
	v_max3_f32 v33, v33, v80, v81
	v_max3_f32 v33, v33, v50, v51
	v_max3_f32 v33, v33, v52, v53
	v_max3_f32 v33, v33, v54, v55
	v_max3_f32 v33, v33, v56, v57
	v_max3_f32 v33, v33, v58, v59
	v_max3_f32 v33, v33, v60, v61
	v_max3_f32 v33, v33, v62, v63
	v_max3_f32 v33, v33, v64, v65
	v_max3_f32 v33, v33, v34, v35
	v_max3_f32 v33, v33, v36, v37
	v_max3_f32 v33, v33, v38, v39
	v_max3_f32 v33, v33, v40, v41
	v_max3_f32 v33, v33, v42, v43
	v_max3_f32 v33, v33, v44, v45
	v_bfe_i32 v224, v135, 27, 1
	v_bfi_b32 v49, v224, v49, v235
	v_max3_f32 v33, v33, v46, v47
	v_max3_f32 v33, v33, v48, v49
	v_cmp_lt_f32_e32 vcc, s33, v33
	s_cbranch_vccz .LBB0_524
	ds_bpermute_b32 v132, v181, v33
	s_waitcnt lgkmcnt(0)
	v_max_f32_e32 v132, v132, v132
	v_max_f32_e32 v33, v33, v132
	v_max_f32_e32 v33, v33, v33
	v_max_f32_e32 v132, 0, v33
	v_exp_f32_e64 v134, -v132
	v_sub_f32_e32 v32, v32, v132
	v_pk_add_f32 v[82:83], v[82:83], v[132:133] op_sel_hi:[1,0] neg_lo:[0,1] neg_hi:[0,1]
	v_pk_add_f32 v[84:85], v[84:85], v[132:133] op_sel_hi:[1,0] neg_lo:[0,1] neg_hi:[0,1]
	v_pk_add_f32 v[86:87], v[86:87], v[132:133] op_sel_hi:[1,0] neg_lo:[0,1] neg_hi:[0,1]
	v_pk_add_f32 v[88:89], v[88:89], v[132:133] op_sel_hi:[1,0] neg_lo:[0,1] neg_hi:[0,1]
	v_pk_add_f32 v[90:91], v[90:91], v[132:133] op_sel_hi:[1,0] neg_lo:[0,1] neg_hi:[0,1]
	v_pk_add_f32 v[92:93], v[92:93], v[132:133] op_sel_hi:[1,0] neg_lo:[0,1] neg_hi:[0,1]
	v_pk_add_f32 v[94:95], v[94:95], v[132:133] op_sel_hi:[1,0] neg_lo:[0,1] neg_hi:[0,1]
	v_pk_add_f32 v[96:97], v[96:97], v[132:133] op_sel_hi:[1,0] neg_lo:[0,1] neg_hi:[0,1]
	v_pk_add_f32 v[66:67], v[66:67], v[132:133] op_sel_hi:[1,0] neg_lo:[0,1] neg_hi:[0,1]
	v_pk_add_f32 v[68:69], v[68:69], v[132:133] op_sel_hi:[1,0] neg_lo:[0,1] neg_hi:[0,1]
	v_pk_add_f32 v[70:71], v[70:71], v[132:133] op_sel_hi:[1,0] neg_lo:[0,1] neg_hi:[0,1]
	v_pk_add_f32 v[72:73], v[72:73], v[132:133] op_sel_hi:[1,0] neg_lo:[0,1] neg_hi:[0,1]
	v_pk_add_f32 v[74:75], v[74:75], v[132:133] op_sel_hi:[1,0] neg_lo:[0,1] neg_hi:[0,1]
	v_pk_add_f32 v[76:77], v[76:77], v[132:133] op_sel_hi:[1,0] neg_lo:[0,1] neg_hi:[0,1]
	v_pk_add_f32 v[78:79], v[78:79], v[132:133] op_sel_hi:[1,0] neg_lo:[0,1] neg_hi:[0,1]
	v_pk_add_f32 v[80:81], v[80:81], v[132:133] op_sel_hi:[1,0] neg_lo:[0,1] neg_hi:[0,1]
	v_pk_add_f32 v[50:51], v[50:51], v[132:133] op_sel_hi:[1,0] neg_lo:[0,1] neg_hi:[0,1]
	v_pk_add_f32 v[52:53], v[52:53], v[132:133] op_sel_hi:[1,0] neg_lo:[0,1] neg_hi:[0,1]
	v_pk_add_f32 v[54:55], v[54:55], v[132:133] op_sel_hi:[1,0] neg_lo:[0,1] neg_hi:[0,1]
	v_pk_add_f32 v[56:57], v[56:57], v[132:133] op_sel_hi:[1,0] neg_lo:[0,1] neg_hi:[0,1]
	v_pk_add_f32 v[58:59], v[58:59], v[132:133] op_sel_hi:[1,0] neg_lo:[0,1] neg_hi:[0,1]
	v_pk_add_f32 v[60:61], v[60:61], v[132:133] op_sel_hi:[1,0] neg_lo:[0,1] neg_hi:[0,1]
	v_pk_add_f32 v[62:63], v[62:63], v[132:133] op_sel_hi:[1,0] neg_lo:[0,1] neg_hi:[0,1]
	v_pk_add_f32 v[64:65], v[64:65], v[132:133] op_sel_hi:[1,0] neg_lo:[0,1] neg_hi:[0,1]
	v_pk_add_f32 v[34:35], v[34:35], v[132:133] op_sel_hi:[1,0] neg_lo:[0,1] neg_hi:[0,1]
	v_pk_add_f32 v[36:37], v[36:37], v[132:133] op_sel_hi:[1,0] neg_lo:[0,1] neg_hi:[0,1]
	v_pk_add_f32 v[38:39], v[38:39], v[132:133] op_sel_hi:[1,0] neg_lo:[0,1] neg_hi:[0,1]
	v_pk_add_f32 v[40:41], v[40:41], v[132:133] op_sel_hi:[1,0] neg_lo:[0,1] neg_hi:[0,1]
	v_pk_add_f32 v[42:43], v[42:43], v[132:133] op_sel_hi:[1,0] neg_lo:[0,1] neg_hi:[0,1]
	v_pk_add_f32 v[44:45], v[44:45], v[132:133] op_sel_hi:[1,0] neg_lo:[0,1] neg_hi:[0,1]
	v_pk_add_f32 v[46:47], v[46:47], v[132:133] op_sel_hi:[1,0] neg_lo:[0,1] neg_hi:[0,1]
	v_pk_add_f32 v[48:49], v[48:49], v[132:133] op_sel_hi:[1,0] neg_lo:[0,1] neg_hi:[0,1]
	v_pk_mul_f32 v[14:15], v[14:15], v[134:135] op_sel_hi:[1,0]
	v_pk_mul_f32 v[12:13], v[12:13], v[134:135] op_sel_hi:[1,0]
	v_pk_mul_f32 v[10:11], v[10:11], v[134:135] op_sel_hi:[1,0]
	v_pk_mul_f32 v[8:9], v[8:9], v[134:135] op_sel_hi:[1,0]
	v_pk_mul_f32 v[6:7], v[6:7], v[134:135] op_sel_hi:[1,0]
	v_pk_mul_f32 v[4:5], v[4:5], v[134:135] op_sel_hi:[1,0]
	v_pk_mul_f32 v[2:3], v[2:3], v[134:135] op_sel_hi:[1,0]
	v_pk_mul_f32 v[0:1], v[0:1], v[134:135] op_sel_hi:[1,0]
	v_pk_mul_f32 v[30:31], v[30:31], v[134:135] op_sel_hi:[1,0]
	v_pk_mul_f32 v[28:29], v[28:29], v[134:135] op_sel_hi:[1,0]
	v_pk_mul_f32 v[26:27], v[26:27], v[134:135] op_sel_hi:[1,0]
	v_pk_mul_f32 v[24:25], v[24:25], v[134:135] op_sel_hi:[1,0]
	v_pk_mul_f32 v[22:23], v[22:23], v[134:135] op_sel_hi:[1,0]
	v_pk_mul_f32 v[20:21], v[20:21], v[134:135] op_sel_hi:[1,0]
	v_pk_mul_f32 v[18:19], v[18:19], v[134:135] op_sel_hi:[1,0]
	v_pk_mul_f32 v[16:17], v[16:17], v[134:135] op_sel_hi:[1,0]
	v_mul_f32_e32 v184, v184, v134
